# GEMM phase prologues: all 14 first-tile LDS-DMA groups issued before the first wait (second batch was issued only after the first batch landed + barrier: two dependent cold round trips per GEMM phase)
# speedup vs baseline: 1.0036x; 1.0036x over previous
.LBB0_66:
	s_mul_i32 s6, s82, 0x600000
	s_mul_hi_i32 s2, s82, 0x600000
	s_add_u32 s6, s24, s6
	s_addc_u32 s2, s25, s2
	s_add_u32 s42, s6, 0x18480000
	s_addc_u32 s43, s2, 0
	s_add_u32 s26, s24, 0xc180000
	s_addc_u32 s27, s25, 0
	v_readfirstlane_b32 s2, v208
	s_cmpk_gt_i32 s28, 0x5ff
	v_and_b32_e32 v143, 15, v208
	s_cbranch_scc1 .LBB0_86
	v_lshlrev_b32_e32 v0, 4, v208
	v_add_u32_e32 v2, 0x2000, v0
	v_ashrrev_i32_e32 v3, 31, v2
	v_lshrrev_b32_e32 v3, 22, v3
	v_add_u32_e32 v3, v2, v3
	v_ashrrev_i32_e32 v10, 10, v3
	v_mul_i32_i24_e32 v3, 0x400, v10
	v_sub_u32_e32 v2, v2, v3
	v_lshrrev_b32_e32 v3, 4, v2
	v_bitop3_b32 v2, v3, v2, 32 bitop3:0x6c
	v_ashrrev_i32_e32 v3, 31, v2
	v_lshrrev_b32_e32 v3, 26, v3
	v_add_u32_e32 v3, v2, v3
	v_lshlrev_b32_e32 v4, 3, v10
	v_ashrrev_i32_e32 v11, 6, v3
	v_and_b32_e32 v4, -16, v4
	v_add_u32_e32 v4, v11, v4
	v_and_b32_e32 v5, 3, v11
	s_mov_b32 s17, 0x1fffe0
	s_waitcnt vmcnt(0)
	v_lshrrev_b32_e32 v6, 2, v4
	v_lshlrev_b32_e32 v7, 1, v4
	v_and_b32_e32 v3, 0xc0, v3
	v_and_or_b32 v5, v4, s17, v5
	v_and_b32_e32 v6, 4, v6
	v_and_b32_e32 v7, 24, v7
	v_sub_u32_e32 v2, v2, v3
	v_or3_b32 v5, v5, v6, v7
	v_lshlrev_b32_e32 v6, 5, v10
	v_ashrrev_i16_sdwa v2, v233, sext(v2) dst_sel:DWORD dst_unused:UNUSED_PAD src0_sel:DWORD src1_sel:BYTE_0
	v_and_b32_e32 v6, 32, v6
	v_bfe_i32 v12, v2, 0, 16
	v_add_lshl_u32 v2, v6, v12, 1
	v_lshl_add_u32 v130, v5, 11, v2
	v_lshl_add_u32 v132, v4, 11, v2
	v_bfe_i32 v2, v208, 27, 1
	v_lshrrev_b32_e32 v2, 22, v2
	v_add_u32_e32 v2, v0, v2
	v_and_b32_e32 v2, 0xfffffc00, v2
	v_sub_u32_e32 v0, v0, v2
	v_lshrrev_b32_e32 v2, 4, v0
	v_ashrrev_i32_e32 v3, 31, v208
	v_bitop3_b32 v0, v2, v0, 32 bitop3:0x6c
	v_lshrrev_b32_e32 v3, 26, v3
	v_ashrrev_i32_e32 v2, 31, v0
	v_add_u32_e32 v3, v208, v3
	v_lshrrev_b32_e32 v2, 26, v2
	v_ashrrev_i32_e32 v14, 6, v3
	v_add_u32_e32 v2, v0, v2
	v_lshlrev_b32_e32 v3, 3, v14
	v_ashrrev_i32_e32 v13, 6, v2
	v_and_b32_e32 v3, -16, v3
	v_add_u32_e32 v3, v13, v3
	v_and_b32_e32 v4, 3, v13
	v_and_or_b32 v4, v3, s17, v4
	s_ashr_i32 s17, s28, 31
	s_lshr_b32 s18, s17, 29
	s_add_i32 s18, s28, s18
	s_ashr_i32 s6, s2, 6
	s_ashr_i32 s19, s18, 3
	s_and_b32 s18, s18, -8
	s_ashr_i32 s15, s2, 8
	s_lshl_b32 s16, s6, 10
	s_sub_i32 s18, s28, s18
	s_cmp_lt_i32 s18, 0
	s_movk_i32 s72, 0xc1
	s_cselect_b32 s20, s72, 0xc0
	s_mul_i32 s18, s18, s20
	s_add_i32 s18, s18, s19
	s_mul_hi_i32 s19, s18, 0x2aaaaaab
	s_lshr_b32 s20, s19, 31
	s_ashr_i32 s19, s19, 4
	s_add_i32 s19, s19, s20
	s_lshl_b32 s20, s19, 3
	s_mulk_i32 s19, 0x60
	s_sub_i32 s18, s18, s19
	s_bfe_i32 s19, s18, 0x80000
	s_bfe_u32 s19, s19, 0x3000c
	s_add_i32 s19, s18, s19
	s_bfe_i32 s21, s19, 0x80000
	s_and_b32 s19, s19, 0xf8
	s_sub_i32 s18, s18, s19
	s_sext_i32_i16 s21, s21
	s_sext_i32_i8 s18, s18
	v_lshrrev_b32_e32 v5, 2, v3
	v_lshlrev_b32_e32 v6, 1, v3
	v_and_b32_e32 v2, 0xc0, v2
	s_lshr_b32 s38, s21, 3
	s_add_i32 s88, s20, s18
	v_and_b32_e32 v5, 4, v5
	v_and_b32_e32 v6, 24, v6
	v_sub_u32_e32 v0, v0, v2
	s_ashr_i32 s89, s88, 31
	s_bfe_i64 s[18:19], s[38:39], 0x100000
	v_or3_b32 v4, v4, v5, v6
	v_lshlrev_b32_e32 v5, 5, v14
	v_ashrrev_i16_sdwa v0, v233, sext(v0) dst_sel:DWORD dst_unused:UNUSED_PAD src0_sel:DWORD src1_sel:BYTE_0
	s_lshl_b64 s[20:21], s[88:89], 19
	s_lshl_b64 s[18:19], s[18:19], 19
	v_and_b32_e32 v5, 32, v5
	v_bfe_i32 v15, v0, 0, 16
	s_add_u32 s92, s42, s18
	v_add_lshl_u32 v2, v5, v15, 1
	s_addc_u32 s93, s43, s19
	s_add_i32 s18, s16, 0
	v_lshl_add_u32 v0, v4, 11, v2
	s_add_i32 m0, s18, 0x10000
	v_lshl_add_u32 v134, v3, 11, v2
	global_load_lds_dwordx4 v0, s[92:93]
	s_add_i32 m0, s18, 0x12000
	s_add_u32 s22, s92, 0x40000
	global_load_lds_dwordx4 v130, s[92:93]
	s_addc_u32 s23, s93, 0
	s_add_i32 m0, s18, 0x14000
	v_mov_b32_e32 v131, v1
	global_load_lds_dwordx4 v0, s[22:23]
	s_add_i32 m0, s18, 0x16000
	s_add_u32 s90, s36, s20
	s_addc_u32 s91, s37, s21
	s_add_i32 s19, s18, 0x2000
	global_load_lds_dwordx4 v130, s[22:23]
	s_mov_b32 m0, s18
	s_add_u32 s22, s90, 0x40000
	global_load_lds_dwordx4 v134, s[90:91]
	s_mov_b32 m0, s19
	s_addc_u32 s23, s91, 0
	s_add_i32 s20, s18, 0x4000
	global_load_lds_dwordx4 v132, s[90:91]
	s_mov_b32 m0, s20
	s_add_i32 s21, s18, 0x6000
	global_load_lds_dwordx4 v134, s[22:23]
	s_mov_b32 m0, s21
	v_mov_b32_e32 v135, v1
	global_load_lds_dwordx4 v132, s[22:23]
	v_mov_b32_e32 v133, v1
	v_lshl_add_u64 v[8:9], s[92:93], 0, v[0:1]
	v_lshl_add_u64 v[6:7], s[92:93], 0, v[130:131]
	v_lshl_add_u64 v[2:3], s[90:91], 0, v[134:135]
	v_lshl_add_u64 v[4:5], s[90:91], 0, v[132:133]
	s_add_i32 m0, s18, 0x18000
	v_lshl_add_u64 v[8:9], v[8:9], 0, s[34:35]
	global_load_lds_dwordx4 v[8:9], off
	v_lshl_add_u64 v[6:7], v[6:7], 0, s[34:35]
	s_add_i32 m0, s18, 0x1a000
	s_add_i32 s23, s18, 0x8000
	s_add_i32 s29, s18, 0xa000
	s_sext_i32_i8 s83, s38
	global_load_lds_dwordx4 v[6:7], off
	v_lshl_add_u64 v[2:3], v[2:3], 0, s[34:35]
	s_mov_b32 m0, s23
	s_add_u32 s38, s92, 0x40080
	global_load_lds_dwordx4 v[2:3], off
	v_lshl_add_u64 v[2:3], v[4:5], 0, s[34:35]
	s_mov_b32 m0, s29
	s_addc_u32 s39, s93, 0
	global_load_lds_dwordx4 v[2:3], off
	s_add_i32 m0, s18, 0x1c000
	v_lshl_add_u64 v[2:3], s[38:39], 0, v[0:1]
	global_load_lds_dwordx4 v[2:3], off
	v_lshl_add_u64 v[2:3], s[38:39], 0, v[130:131]
	s_add_i32 m0, s18, 0x1e000
	global_load_lds_dwordx4 v[2:3], off
	s_cmp_eq_u32 s15, 1
	s_cselect_b64 s[44:45], -1, 0
	s_cmp_lg_u32 s15, 1
	s_cbranch_scc1 .LBB0_69
	s_barrier
.LBB0_69:
	v_bfe_u32 v147, v208, 4, 2
	v_lshlrev_b32_e32 v16, 6, v143
	v_lshlrev_b32_e32 v17, 2, v143
	s_and_b32 s22, s6, 3
	v_lshl_or_b32 v16, v147, 4, v16
	s_lshl_b32 s6, s15, 13
	v_and_b32_e32 v17, 32, v17
	v_bitop3_b32 v18, s6, v16, v17 bitop3:0xf6
	s_lshl_b32 s6, s22, 12
	s_waitcnt vmcnt(8)
	s_barrier
	s_cmpk_lt_u32 s2, 0x100
	v_lshlrev_b32_e32 v2, 14, v14
	v_and_b32_e32 v2, 0xffff8000, v2
	v_lshl_add_u32 v2, v13, 11, v2
	v_and_b32_e32 v3, 1, v14
	v_lshl_or_b32 v2, v3, 6, v2
	v_lshl_add_u32 v136, v15, 1, v2
	v_lshlrev_b32_e32 v2, 14, v10
	v_and_b32_e32 v2, 0xffff8000, v2
	s_waitcnt vmcnt(6)
	v_lshl_add_u32 v2, v11, 11, v2
	v_and_b32_e32 v3, 1, v10
	v_lshl_or_b32 v2, v3, 6, v2
	v_bitop3_b32 v151, s6, v16, v17 bitop3:0xf6
	s_cselect_b64 s[46:47], -1, 0
	s_ashr_i32 s48, s12, 31
	v_mov_b32_e32 v137, v1
	v_lshl_add_u32 v138, v12, 1, v2
	v_mov_b32_e32 v139, v1
	s_mov_b32 s81, 0
	v_add_u32_e32 v153, 0, v18
	s_barrier
	s_branch .LBB0_72

.LBB0_171:
	s_add_u32 s44, s24, 0x1a0f4c00
	s_addc_u32 s45, s25, 0
	s_add_u32 s62, s24, 0x4080000
	s_waitcnt vmcnt(0)
	v_and_b32_e32 v160, 15, v208
	s_addc_u32 s63, s25, 0
	s_andn2_b64 vcc, exec, s[26:27]
	s_cbranch_vccnz .LBB0_211
	v_bfe_i32 v3, v208, 27, 1
	v_lshlrev_b32_e32 v2, 4, v208
	v_lshrrev_b32_e32 v3, 22, v3
	v_add_u32_e32 v3, v2, v3
	v_and_b32_e32 v3, 0xfffffc00, v3
	v_sub_u32_e32 v3, v2, v3
	v_ashrrev_i32_e32 v0, 31, v208
	v_lshrrev_b32_e32 v4, 4, v3
	v_lshrrev_b32_e32 v0, 26, v0
	v_bitop3_b32 v3, v4, v3, 32 bitop3:0x6c
	v_add_u32_e32 v0, v208, v0
	v_ashrrev_i32_e32 v5, 31, v3
	v_ashrrev_i32_e32 v0, 6, v0
	v_lshrrev_b32_e32 v5, 26, v5
	v_lshlrev_b32_e32 v4, 3, v0
	v_add_u32_e32 v5, v3, v5
	v_and_b32_e32 v4, -16, v4
	v_ashrrev_i32_e32 v6, 6, v5
	v_lshlrev_b32_e32 v0, 5, v0
	v_add_u32_e32 v4, v6, v4
	v_and_b32_e32 v14, 32, v0
	v_and_b32_e32 v0, 0xc0, v5
	v_sub_u32_e32 v0, v3, v0
	v_lshlrev_b32_e32 v3, 1, v4
	v_lshrrev_b32_e32 v5, 2, v4
	v_and_b32_e32 v6, 3, v6
	s_mov_b32 s16, 0x7fffffe0
	v_ashrrev_i16_sdwa v0, v233, sext(v0) dst_sel:DWORD dst_unused:UNUSED_PAD src0_sel:DWORD src1_sel:BYTE_0
	v_and_b32_e32 v3, 24, v3
	v_and_b32_e32 v5, 4, v5
	v_and_or_b32 v6, v4, s16, v6
	v_bfe_i32 v15, v0, 0, 16
	v_or3_b32 v3, v6, v5, v3
	v_add_u32_e32 v0, v14, v15
	v_mul_lo_u32 v16, s15, v4
	v_mul_lo_u32 v3, s15, v3
	v_add_u32_e32 v2, 0x2000, v2
	v_add_lshl_u32 v146, v16, v0, 1
	v_add_lshl_u32 v0, v3, v0, 1
	v_ashrrev_i32_e32 v3, 31, v2
	v_lshrrev_b32_e32 v3, 22, v3
	v_add_u32_e32 v3, v2, v3
	v_ashrrev_i32_e32 v3, 10, v3
	v_mul_i32_i24_e32 v4, 0x400, v3
	v_sub_u32_e32 v2, v2, v4
	v_lshrrev_b32_e32 v4, 4, v2
	v_bitop3_b32 v2, v4, v2, 32 bitop3:0x6c
	v_ashrrev_i32_e32 v5, 31, v2
	v_lshrrev_b32_e32 v5, 26, v5
	v_lshlrev_b32_e32 v4, 3, v3
	v_add_u32_e32 v5, v2, v5
	v_and_b32_e32 v4, -16, v4
	v_ashrrev_i32_e32 v6, 6, v5
	s_ashr_i32 s6, s2, 6
	v_add_u32_e32 v4, v6, v4
	v_lshlrev_b32_e32 v3, 5, v3
	v_and_b32_e32 v6, 3, v6
	s_lshl_b32 s17, s15, 9
	v_and_b32_e32 v17, 32, v3
	v_and_b32_e32 v3, 0xc0, v5
	v_and_or_b32 v6, v4, s16, v6
	s_ashr_i32 s16, s2, 8
	s_lshl_b32 s26, s15, 8
	s_lshl_b32 s18, s6, 10
	s_mul_i32 s20, s17, s99
	v_sub_u32_e32 v2, v2, v3
	v_lshlrev_b32_e32 v3, 1, v4
	v_lshrrev_b32_e32 v5, 2, v4
	s_mul_hi_i32 s19, s17, s99
	s_add_u32 s92, s42, s20
	v_ashrrev_i16_sdwa v2, v233, sext(v2) dst_sel:DWORD dst_unused:UNUSED_PAD src0_sel:DWORD src1_sel:BYTE_0
	v_and_b32_e32 v3, 24, v3
	v_and_b32_e32 v5, 4, v5
	s_addc_u32 s93, s43, s19
	s_add_i32 s19, s18, 0
	v_bfe_i32 v18, v2, 0, 16
	v_or3_b32 v3, v6, v5, v3
	s_add_i32 m0, s19, 0x10000
	v_add_u32_e32 v2, v17, v18
	v_mul_lo_u32 v3, s15, v3
	global_load_lds_dwordx4 v0, s[92:93]
	s_add_i32 m0, s19, 0x12000
	v_add_lshl_u32 v150, v3, v2, 1
	s_add_u32 s20, s92, s26
	global_load_lds_dwordx4 v150, s[92:93]
	s_addc_u32 s21, s93, 0
	s_add_i32 m0, s19, 0x14000
	s_mul_i32 s23, s17, s48
	global_load_lds_dwordx4 v0, s[20:21]
	s_add_i32 m0, s19, 0x16000
	s_mul_hi_i32 s22, s17, s48
	v_mov_b32_e32 v151, v1
	s_add_u32 s94, s50, s23
	v_lshl_add_u64 v[6:7], s[20:21], 0, v[0:1]
	v_lshl_add_u64 v[8:9], s[20:21], 0, v[150:151]
	global_load_lds_dwordx4 v150, s[20:21]
	s_addc_u32 s95, s51, s22
	s_add_i32 s20, s19, 0x2000
	s_waitcnt lgkmcnt(0)
	v_mul_lo_u32 v19, s15, v4
	s_mov_b32 m0, s19
	s_add_u32 s38, s94, s26
	v_add_lshl_u32 v148, v19, v2, 1
	global_load_lds_dwordx4 v146, s[94:95]
	s_mov_b32 m0, s20
	s_addc_u32 s39, s95, 0
	s_add_i32 s21, s19, 0x4000
	global_load_lds_dwordx4 v148, s[94:95]
	s_mov_b32 m0, s21
	s_add_i32 s22, s19, 0x6000
	global_load_lds_dwordx4 v146, s[38:39]
	s_mov_b32 m0, s22
	v_mov_b32_e32 v147, v1
	global_load_lds_dwordx4 v148, s[38:39]
	v_mov_b32_e32 v149, v1
	s_mov_b32 s27, s80
	v_lshl_add_u64 v[2:3], s[92:93], 0, v[0:1]
	v_lshl_add_u64 v[4:5], s[92:93], 0, v[150:151]
	v_lshl_add_u64 v[10:11], s[94:95], 0, v[146:147]
	v_lshl_add_u64 v[12:13], s[94:95], 0, v[148:149]
	s_add_i32 m0, s19, 0x18000
	v_lshl_add_u64 v[2:3], v[2:3], 0, s[34:35]
	global_load_lds_dwordx4 v[2:3], off
	v_lshl_add_u64 v[2:3], v[4:5], 0, s[34:35]
	s_add_i32 m0, s19, 0x1a000
	s_add_i32 s81, s19, 0x8000
	global_load_lds_dwordx4 v[2:3], off
	v_lshl_add_u64 v[2:3], v[10:11], 0, s[34:35]
	s_mov_b32 m0, s81
	s_add_i32 s83, s19, 0xa000
	global_load_lds_dwordx4 v[2:3], off
	v_lshl_add_u64 v[2:3], v[12:13], 0, s[34:35]
	s_mov_b32 m0, s83
	global_load_lds_dwordx4 v[2:3], off
	s_add_i32 m0, s19, 0x1c000
	v_lshl_add_u64 v[2:3], v[6:7], 0, s[34:35]
	global_load_lds_dwordx4 v[2:3], off
	v_lshl_add_u64 v[2:3], v[8:9], 0, s[34:35]
	s_add_i32 m0, s19, 0x1e000
	global_load_lds_dwordx4 v[2:3], off
	s_cmp_eq_u32 s16, 1
	s_cselect_b64 s[74:75], -1, 0
	s_cmp_lg_u32 s16, 1
	s_cbranch_scc1 .LBB0_174
	s_barrier
.LBB0_174:
	s_and_b32 s23, s6, 3
	s_lshr_b32 s29, s15, 6
	s_lshl_b32 s6, s16, 13
	s_lshl_b32 s38, s23, 12
	s_add_u32 s76, s24, 0x196a0400
	s_addc_u32 s77, s25, 0
	s_waitcnt vmcnt(8)
	s_barrier
	v_bfe_u32 v161, v208, 4, 2
	s_add_i32 s96, s29, -2
	v_lshlrev_b32_e32 v2, 6, v160
	v_lshlrev_b32_e32 v3, 2, v160
	v_lshl_or_b32 v2, v161, 4, v2
	v_and_b32_e32 v3, 32, v3
	v_bitop3_b32 v4, s6, v2, v3 bitop3:0xf6
	v_bitop3_b32 v162, s38, v2, v3 bitop3:0xf6
	v_add_u32_e32 v2, v16, v14
	v_add_lshl_u32 v2, v2, v15, 1
	v_mov_b32_e32 v3, v1
	s_waitcnt vmcnt(6)
	v_lshl_add_u64 v[152:153], s[26:27], 0, v[2:3]
	v_add_u32_e32 v2, v19, v17
	s_cmpk_lt_u32 s2, 0x100
	v_add_lshl_u32 v2, v2, v18, 1
	s_cselect_b64 s[78:79], -1, 0
	s_ashr_i32 s97, s12, 31
	s_ashr_i32 s98, s28, 31
	v_lshl_add_u64 v[154:155], s[26:27], 0, v[2:3]
	s_mov_b32 s27, 0
	v_add_u32_e32 v163, 0, v4
	s_barrier
	s_branch .LBB0_177

.LBB0_234:
	s_mul_i32 s15, s14, 0xb00000
	s_mul_hi_i32 s6, s14, 0xb00000
	s_add_u32 s15, s24, s15
	s_addc_u32 s6, s25, s6
	s_add_u32 s50, s15, 0x14280000
	s_addc_u32 s51, s6, 0
	s_mul_i32 s15, s14, 0x8400
	v_readlane_b32 s88, v255, 21
	s_mul_hi_i32 s6, s14, 0x8400
	v_readlane_b32 s89, v255, 22
	s_add_u32 s44, s88, s15
	s_addc_u32 s45, s89, s6
	s_add_u32 s46, s24, 0x198a4400
	s_addc_u32 s47, s25, 0
	v_and_b32_e32 v177, 15, v208
	s_andn2_b64 vcc, exec, s[26:27]
	v_readlane_b32 s90, v255, 23
	v_readlane_b32 s91, v255, 24
	v_readlane_b32 s92, v255, 25
	v_readlane_b32 s93, v255, 26
	v_readlane_b32 s94, v255, 27
	v_readlane_b32 s95, v255, 28
	s_cbranch_vccnz .LBB0_273
	v_bfe_i32 v3, v208, 27, 1
	v_lshlrev_b32_e32 v2, 4, v208
	v_lshrrev_b32_e32 v3, 22, v3
	v_add_u32_e32 v3, v2, v3
	v_and_b32_e32 v3, 0xfffffc00, v3
	v_sub_u32_e32 v3, v2, v3
	v_lshrrev_b32_e32 v4, 4, v3
	v_ashrrev_i32_e32 v0, 31, v208
	v_bitop3_b32 v3, v4, v3, 32 bitop3:0x6c
	v_lshrrev_b32_e32 v0, 26, v0
	v_ashrrev_i32_e32 v5, 31, v3
	v_add_u32_e32 v0, v208, v0
	v_lshrrev_b32_e32 v5, 26, v5
	v_ashrrev_i32_e32 v0, 6, v0
	v_add_u32_e32 v5, v3, v5
	v_lshlrev_b32_e32 v4, 3, v0
	v_ashrrev_i32_e32 v10, 6, v5
	v_and_b32_e32 v5, 0xc0, v5
	v_and_b32_e32 v4, -16, v4
	v_sub_u32_e32 v3, v3, v5
	v_add_u32_e32 v4, v10, v4
	v_ashrrev_i16_sdwa v3, v233, sext(v3) dst_sel:DWORD dst_unused:UNUSED_PAD src0_sel:DWORD src1_sel:BYTE_0
	s_waitcnt vmcnt(0)
	v_lshlrev_b32_e32 v6, 5, v0
	v_bfe_i32 v11, v3, 0, 16
	v_lshlrev_b32_e32 v3, 1, v4
	v_lshrrev_b32_e32 v5, 2, v4
	v_and_b32_e32 v7, 3, v10
	s_mov_b32 s15, 0x1fffe0
	v_and_b32_e32 v6, 32, v6
	v_and_b32_e32 v3, 24, v3
	v_and_b32_e32 v5, 4, v5
	v_and_or_b32 v7, v4, s15, v7
	v_or3_b32 v3, v7, v5, v3
	v_add_lshl_u32 v5, v6, v11, 1
	v_add_u32_e32 v2, 0x2000, v2
	s_waitcnt vmcnt(0)
	v_lshl_add_u32 v164, v3, 11, v5
	v_ashrrev_i32_e32 v3, 31, v2
	v_lshrrev_b32_e32 v3, 22, v3
	v_add_u32_e32 v3, v2, v3
	v_ashrrev_i32_e32 v12, 10, v3
	v_mul_i32_i24_e32 v3, 0x400, v12
	v_sub_u32_e32 v2, v2, v3
	v_lshrrev_b32_e32 v3, 4, v2
	v_bitop3_b32 v2, v3, v2, 32 bitop3:0x6c
	v_lshl_add_u32 v162, v4, 11, v5
	v_ashrrev_i32_e32 v4, 31, v2
	v_lshrrev_b32_e32 v4, 26, v4
	v_lshlrev_b32_e32 v3, 3, v12
	v_add_u32_e32 v4, v2, v4
	v_and_b32_e32 v3, -16, v3
	v_ashrrev_i32_e32 v13, 6, v4
	s_ashr_i32 s6, s2, 6
	v_add_u32_e32 v3, v13, v3
	v_and_b32_e32 v4, 0xc0, v4
	v_and_b32_e32 v6, 3, v13
	s_ashr_i32 s77, s76, 31
	s_ashr_i32 s41, s40, 31
	v_sub_u32_e32 v2, v2, v4
	v_and_or_b32 v6, v3, s15, v6
	s_ashr_i32 s15, s2, 8
	s_lshl_b32 s29, s6, 10
	s_lshl_b64 s[16:17], s[76:77], 19
	s_lshl_b64 s[18:19], s[40:41], 19
	v_ashrrev_i16_sdwa v2, v233, sext(v2) dst_sel:DWORD dst_unused:UNUSED_PAD src0_sel:DWORD src1_sel:BYTE_0
	s_add_u32 s92, s50, s18
	v_lshlrev_b32_e32 v5, 5, v12
	v_bfe_i32 v14, v2, 0, 16
	v_lshlrev_b32_e32 v2, 1, v3
	v_lshrrev_b32_e32 v4, 2, v3
	s_addc_u32 s93, s51, s19
	s_add_i32 s81, s29, 0
	v_and_b32_e32 v5, 32, v5
	v_and_b32_e32 v2, 24, v2
	v_and_b32_e32 v4, 4, v4
	s_add_i32 m0, s81, 0x10000
	v_or3_b32 v2, v6, v4, v2
	v_add_lshl_u32 v4, v5, v14, 1
	global_load_lds_dwordx4 v164, s[92:93]
	s_add_i32 m0, s81, 0x12000
	v_lshl_add_u32 v168, v2, 11, v4
	s_add_u32 s18, s92, 0x40000
	global_load_lds_dwordx4 v168, s[92:93]
	s_addc_u32 s19, s93, 0
	s_add_i32 m0, s81, 0x14000
	v_lshl_add_u32 v166, v3, 11, v4
	global_load_lds_dwordx4 v164, s[18:19]
	s_add_i32 m0, s81, 0x16000
	s_add_u32 s42, s36, s16
	s_addc_u32 s43, s37, s17
	s_add_i32 s83, s81, 0x2000
	global_load_lds_dwordx4 v168, s[18:19]
	s_mov_b32 m0, s81
	s_add_u32 s18, s42, 0x40000
	global_load_lds_dwordx4 v162, s[42:43]
	s_mov_b32 m0, s83
	s_addc_u32 s19, s43, 0
	s_add_i32 s16, s81, 0x4000
	global_load_lds_dwordx4 v166, s[42:43]
	s_mov_b32 m0, s16
	s_add_i32 s17, s81, 0x6000
	global_load_lds_dwordx4 v162, s[18:19]
	s_mov_b32 m0, s17
	v_mov_b32_e32 v165, v1
	global_load_lds_dwordx4 v166, s[18:19]
	v_mov_b32_e32 v169, v1
	v_mov_b32_e32 v163, v1
	v_mov_b32_e32 v167, v1
	v_lshl_add_u64 v[8:9], s[92:93], 0, v[164:165]
	v_lshl_add_u64 v[6:7], s[92:93], 0, v[168:169]
	v_lshl_add_u64 v[2:3], s[42:43], 0, v[162:163]
	v_lshl_add_u64 v[4:5], s[42:43], 0, v[166:167]
	s_add_i32 m0, s81, 0x18000
	v_lshl_add_u64 v[8:9], v[8:9], 0, s[34:35]
	global_load_lds_dwordx4 v[8:9], off
	v_lshl_add_u64 v[6:7], v[6:7], 0, s[34:35]
	s_add_i32 m0, s81, 0x1a000
	s_add_i32 s19, s81, 0x8000
	s_add_i32 s20, s81, 0xa000
	global_load_lds_dwordx4 v[6:7], off
	v_lshl_add_u64 v[2:3], v[2:3], 0, s[34:35]
	s_mov_b32 m0, s19
	s_add_u32 s22, s92, 0x40080
	global_load_lds_dwordx4 v[2:3], off
	v_lshl_add_u64 v[2:3], v[4:5], 0, s[34:35]
	s_mov_b32 m0, s20
	s_addc_u32 s23, s93, 0
	global_load_lds_dwordx4 v[2:3], off
	s_add_i32 m0, s81, 0x1c000
	v_lshl_add_u64 v[2:3], s[22:23], 0, v[164:165]
	global_load_lds_dwordx4 v[2:3], off
	v_lshl_add_u64 v[2:3], s[22:23], 0, v[168:169]
	s_add_i32 m0, s81, 0x1e000
	global_load_lds_dwordx4 v[2:3], off
	s_cmp_eq_u32 s15, 1
	s_cselect_b64 s[62:63], -1, 0
	s_cmp_lg_u32 s15, 1
	s_cbranch_scc1 .LBB0_237
	s_barrier
.LBB0_237:
	s_add_u32 s68, s24, 0x19b69c00
	s_addc_u32 s69, s25, 0
	s_and_b32 s18, s6, 3
	s_lshl_b32 s6, s15, 13
	s_lshl_b32 s21, s18, 12
	s_waitcnt vmcnt(8)
	s_barrier
	v_bfe_u32 v179, v208, 4, 2
	v_lshlrev_b32_e32 v2, 6, v177
	v_lshlrev_b32_e32 v3, 2, v177
	v_lshl_or_b32 v2, v179, 4, v2
	v_and_b32_e32 v3, 32, v3
	v_bitop3_b32 v4, s6, v2, v3 bitop3:0xf6
	v_bitop3_b32 v181, s21, v2, v3 bitop3:0xf6
	v_lshlrev_b32_e32 v2, 14, v0
	v_and_b32_e32 v2, 0xffff8000, v2
	v_lshl_add_u32 v2, v10, 11, v2
	v_and_b32_e32 v0, 1, v0
	s_cmpk_lt_u32 s2, 0x100
	v_lshl_or_b32 v0, v0, 6, v2
	s_cselect_b64 s[74:75], -1, 0
	s_ashr_i32 s21, s12, 31
	s_ashr_i32 s22, s28, 31
	v_lshl_add_u32 v170, v11, 1, v0
	v_lshlrev_b32_e32 v0, 14, v12
	s_add_u32 s78, s44, 0x2c00
	v_and_b32_e32 v0, 0xffff8000, v0
	s_waitcnt vmcnt(6)
	s_addc_u32 s79, s45, 0
	v_lshl_add_u32 v0, v13, 11, v0
	v_and_b32_e32 v2, 1, v12
	s_add_u32 s26, s44, 0x5800
	v_lshl_or_b32 v0, v2, 6, v0
	s_addc_u32 s27, s45, 0
	v_mov_b32_e32 v171, v1
	v_lshl_add_u32 v172, v14, 1, v0
	v_mov_b32_e32 v173, v1
	s_mov_b32 s23, 0
	v_add_u32_e32 v189, 0, v4
	s_barrier
	s_branch .LBB0_240
